# B loop: softmax scale folded into q gain (prep_phase) and running max folded into QK accumulator init; A,B,C loops trimmed as before
# speedup vs baseline: 1.0267x; 1.0064x over previous
;     DI const float* in(int i) const { return (const float*)gp(i); }
;     DI unsigned char* ws() const { return (unsigned char*)gp(35); }
; DI int fresh_tid(const Params& P) { int t = P.tid; asm volatile("" : "+v"(t)); return t; }
; DI void prep_phase(const Params& P, int l) {
;     const int tid_ = fresh_tid(P);
;     const int wid = tid_ >> 6, lane = tid_ & 63, half = lane >> 5, j = lane & 31;
;     bf16_t* z = (bf16_t*)(P.ws() + WS_Z); const f32x2* rope = (const f32x2*)(P.ws() + WS_ROPE);
;     const float* gbq = P.in(13) + l * 128; const float* gbk = P.in(14) + l * 128; const float* gcq = P.in(15) + l * 512; const float* gckv = P.in(16) + l * 256;
;     float gq[4], gk[4], gcqv[8], gckvv[4];
; #pragma unroll
;     for (int i = 0; i < 4; ++i) { gq[i] = gbq[j + 32 * i]; gk[i] = gbk[j + 32 * i]; gckvv[i] = gckv[lane * 4 + i]; }
; #pragma unroll
;     for (int q = 0; q < 8; ++q) gcqv[q] = gcq[lane * 8 + q];
;     constexpr int NTK = 2;
;     const int stride = gridDim.x * 8;
;     for (int t0 = blockIdx.x * 8 + wid; t0 < T; t0 += NTK * stride) {
;         unsigned hv[NTK][5][4], kr1[NTK], kr2[NTK]; u32x4 wq[NTK]; u32x2 wkv[NTK]; f32x2 cr[NTK], cc[NTK], ct[NTK];
; #pragma unroll
;         for (int r = 0; r < NTK; ++r) { const int t = t0 + r * stride; const bf16_t* zr = z + (size_t)t * LDZ;
;             const int s = t < 4096 ? t : (t < 8192 ? t - 4096 : t - 8192);
;             cr[r] = rope[(s >> 6) * 32 + j]; cc[r] = rope[(s & 63) * 32 + j]; ct[r] = rope[s * 32 + j];
; #pragma unroll
;             for (int it = 0; it < 5; ++it) { const int hh = it * 2 + half; const int base = hh < 8 ? ZC_BQ + hh * 128 : ZC_BK + (hh - 8) * 128;
; #pragma unroll
;                 for (int i = 0; i < 4; ++i) hv[r][it][i] = zr[base + j + 32 * i]; }
;             wq[r] = *(const u32x4*)(zr + ZC_CQA + lane * 8); wkv[r] = *(const u32x2*)(zr + ZC_CKVA + lane * 4);
;             kr1[r] = zr[ZC_CKR + j]; kr2[r] = zr[ZC_CKR + 32 + j]; }
.LBB0_539:
	s_lshl_b32 s0, s64, 7
	s_ashr_i32 s1, s0, 31
	v_writelane_b32 v242, s0, 37
	s_cmp_lg_u32 s83, 1
	s_nop 0
	v_writelane_b32 v242, s1, 38
	s_cbranch_scc1 .LBB0_548
	v_mov_b32_e32 v0, v193
	s_waitcnt vmcnt(7)
	v_mov_b32_e32 v2, s86
	ds_read_b64 v[2:3], v2
	v_readlane_b32 s4, v242, 15
	v_readlane_b32 s6, v242, 16
	s_waitcnt lgkmcnt(0)
	v_readfirstlane_b32 s0, v2
	v_mov_b32_e32 v2, s4
	v_readfirstlane_b32 s1, v3
	ds_read2_b64 v[2:5], v2 offset1:1
	s_waitcnt lgkmcnt(0)
	v_readfirstlane_b32 s11, v2
	v_mov_b32_e32 v2, s6
	v_readfirstlane_b32 s5, v3
	v_readfirstlane_b32 s4, v5
	v_readfirstlane_b32 s10, v4
	ds_read2_b64 v[2:5], v2 offset1:1
	v_readlane_b32 s6, v242, 6
	s_waitcnt lgkmcnt(0)
	v_readfirstlane_b32 s14, v2
	v_ashrrev_i32_e32 v2, 6, v0
	s_waitcnt vmcnt(4)
	v_add_u32_e32 v23, s6, v2
	s_movk_i32 s6, 0x4000
	v_readfirstlane_b32 s12, v3
	v_readfirstlane_b32 s15, v5
	v_readfirstlane_b32 s16, v4
	v_cmp_gt_i32_e32 vcc, s6, v23
	s_and_saveexec_b64 s[6:7], vcc
	s_cbranch_execz .LBB0_547
	s_lshl_b32 s24, s64, 9
	s_lshl_b32 s28, s64, 8
	s_ashr_i32 s25, s24, 31
	s_ashr_i32 s29, s28, 31
	v_readlane_b32 s36, v242, 37
	s_add_u32 s8, s0, 0x4c80000
	v_readlane_b32 s37, v242, 38
	s_addc_u32 s9, s1, 0
	s_lshl_b64 s[36:37], s[36:37], 2
	s_add_u32 s50, s11, s36
	s_addc_u32 s51, s5, s37
	s_add_u32 s10, s10, s36
	s_addc_u32 s11, s4, s37
	s_lshl_b64 s[4:5], s[28:29], 2
	v_and_b32_e32 v15, 63, v0
	s_add_u32 s4, s16, s4
	v_and_b32_e32 v22, 31, v0
	s_addc_u32 s5, s15, s5
	v_lshlrev_b32_e32 v17, 4, v15
	v_lshlrev_b32_e32 v0, 2, v22
	global_load_dwordx4 v[2:5], v17, s[4:5]
	global_load_dword v172, v0, s[50:51]
	global_load_dword v173, v0, s[10:11]
	global_load_dword v174, v0, s[50:51] offset:128
	global_load_dword v175, v0, s[10:11] offset:128
	global_load_dword v176, v0, s[50:51] offset:256
	global_load_dword v177, v0, s[10:11] offset:256
	global_load_dword v178, v0, s[10:11] offset:384
	global_load_dword v179, v0, s[50:51] offset:384
	s_lshl_b64 s[4:5], s[24:25], 2
	s_add_u32 s4, s14, s4
	s_addc_u32 s5, s12, s5
	v_lshlrev_b32_e32 v0, 5, v15
	global_load_dwordx4 v[6:9], v0, s[4:5]
	global_load_dwordx4 v[10:13], v0, s[4:5] offset:16
	v_lshlrev_b32_e32 v14, 2, v15
	v_and_or_b32 v19, v14, s31, v22
	v_lshlrev_b32_e32 v16, 3, v15
	s_add_u32 s52, s0, 0x28c80000
	v_or_b32_e32 v0, 0xc00, v19
	v_cmp_gt_u32_e32 vcc, 32, v15
	v_or_b32_e32 v18, 0xc20, v19
	v_or_b32_e32 v20, 0xc40, v19
	v_or_b32_e32 v74, 0xc60, v19
	v_or_b32_e32 v76, 0xd00, v19
	v_or_b32_e32 v78, 0xd20, v19
	v_or_b32_e32 v80, 0xd40, v19
	v_or_b32_e32 v82, 0xd60, v19
	v_or_b32_e32 v84, 0xe00, v19
	v_or_b32_e32 v86, 0xe20, v19
	v_or_b32_e32 v88, 0xe40, v19
	v_or_b32_e32 v90, 0xe60, v19
	v_or_b32_e32 v92, 0xf00, v19
	v_or_b32_e32 v94, 0xf20, v19
	v_or_b32_e32 v96, 0xf40, v19
	v_or_b32_e32 v98, 0xf60, v19
	v_lshlrev_b32_e32 v15, 1, v19
	v_mov_b64_e32 v[26:27], s[0:1]
	s_addc_u32 s53, s1, 0
	v_or_b32_e32 v24, 0x18c0, v15
	v_mov_b32_e32 v25, v1
	v_mad_i64_i32 v[26:27], s[0:1], v23, s92, v[26:27]
	v_or_b32_e32 v28, 0x1880, v15
	v_mov_b32_e32 v29, v1
	v_or_b32_e32 v30, 0x1840, v15
	v_mov_b32_e32 v31, v1
	v_or_b32_e32 v32, 0x1800, v15
	v_mov_b32_e32 v33, v1
	s_waitcnt vmcnt(14)
	v_or_b32_e32 v34, 0x4c818c0, v15
	v_mov_b32_e32 v35, v1
	v_or_b32_e32 v36, 0x4c81880, v15
	v_mov_b32_e32 v37, v1
	s_waitcnt vmcnt(13)
	v_or_b32_e32 v38, 0x4c81840, v15
	v_mov_b32_e32 v39, v1
	v_lshlrev_b32_e32 v40, 1, v22
	v_mov_b32_e32 v41, v1
	v_or_b32_e32 v42, 0x4c82800, v16
	v_mov_b32_e32 v43, v1
	v_or_b32_e32 v44, 0x4c82400, v17
	v_mov_b32_e32 v45, v1
	v_or_b32_e32 v46, 0x4c81ec0, v15
	v_mov_b32_e32 v47, v1
	v_or_b32_e32 v48, 0x4c81e80, v15
	v_mov_b32_e32 v49, v1
	s_waitcnt vmcnt(12)
	v_or_b32_e32 v50, 0x4c81e40, v15
	v_mov_b32_e32 v51, v1
	v_or_b32_e32 v52, 0x4c81e00, v15
	v_mov_b32_e32 v53, v1
	s_waitcnt vmcnt(11)
	v_or_b32_e32 v54, 0x4c81cc0, v15
	v_mov_b32_e32 v55, v1
	v_or_b32_e32 v56, 0x4c81c80, v15
	v_mov_b32_e32 v57, v1
	v_or_b32_e32 v58, 0x4c81c40, v15
	v_mov_b32_e32 v59, v1
	v_or_b32_e32 v60, 0x4c81c00, v15
	v_mov_b32_e32 v61, v1
	v_or_b32_e32 v62, 0x4c81ac0, v15
	v_mov_b32_e32 v63, v1
	v_or_b32_e32 v64, 0x4c81a80, v15
	v_mov_b32_e32 v65, v1
	v_or_b32_e32 v66, 0x4c81a40, v15
	v_mov_b32_e32 v67, v1
	v_or_b32_e32 v68, 0x4c81a00, v15
	v_mov_b32_e32 v69, v1
	s_mov_b64 s[54:55], 0
	v_lshlrev_b32_e32 v0, 1, v0
	v_lshlrev_b32_e32 v70, 1, v18
	v_lshlrev_b32_e32 v72, 1, v20
	v_lshlrev_b32_e32 v74, 1, v74
	v_lshlrev_b32_e32 v76, 1, v76
	v_lshlrev_b32_e32 v78, 1, v78
	v_lshlrev_b32_e32 v80, 1, v80
	v_lshlrev_b32_e32 v82, 1, v82
	v_lshlrev_b32_e32 v84, 1, v84
	v_lshlrev_b32_e32 v86, 1, v86
	v_lshlrev_b32_e32 v88, 1, v88
	v_lshlrev_b32_e32 v90, 1, v90
	v_lshlrev_b32_e32 v92, 1, v92
	v_lshlrev_b32_e32 v94, 1, v94
	v_lshlrev_b32_e32 v96, 1, v96
	v_lshlrev_b32_e32 v98, 1, v98
	v_lshlrev_b32_e32 v100, 1, v16
	v_lshlrev_b32_e32 v102, 1, v14
	s_waitcnt vmcnt(0)
	v_mul_f32_e32 v172, 0x3e0293ee, v172
	v_mul_f32_e32 v174, 0x3e0293ee, v174
	v_mul_f32_e32 v176, 0x3e0293ee, v176
	v_mul_f32_e32 v179, 0x3e0293ee, v179
	s_branch .LBB0_543

; #define DMA(buf, k0) do { _Pragma("unroll") for (int _i = 0; _i < NI; ++_i) { \
;         char* _d = (_i < 2) ? V_lds + (buf) * SHM_V + (wu + 8 * _i) * 1024 : K_lds + (buf) * SHM_K + (wu + 8 * _i - 16) * 1024; \
;         __builtin_amdgcn_global_load_lds((const unsigned*)(sp[_i] + (size_t)(k0) * sld[_i]), (LAS unsigned*)_d, 16, 0, 0); } } while (0)
; template <int DQK, int MODE>
; DI void attn_body(const AttnArgs& a, char* lds) {
;     ...
;     float m_reg = -1e30f, l_reg = 0; f32x16 o[4] = {}; bf16x8 qr[NQR];
;     ...
;     DMA(0, 0); asm volatile("s_waitcnt vmcnt(0)" ::: "memory"); __syncthreads();
;     if (wid >= 4) __builtin_amdgcn_s_setprio(1);
; #pragma unroll 1
;     for (int j = 0; j < NT; ++j) {
;         const int cur = j & 1;
;         if (j + 1 < NT) DMA(cur ^ 1, (j + 1) * 64);
.Lprio_skip_3:
	s_or_b64 exec, exec, s[52:53]
	v_subrev_u32_e32 v216, s89, v130
	v_subrev_u32_e32 v217, s89, v132
	v_subrev_u32_e32 v218, s89, v134
	v_subrev_u32_e32 v219, s89, v136
	s_add_u32 s89, s89, 0x170000
	s_addc_u32 s90, s90, 0
	v_mov_b32_e32 v196, 0
	v_mov_b32_e32 v197, 0
	v_mov_b32_e32 v198, 0
	v_mov_b32_e32 v199, 0
	v_mov_b32_e32 v200, 0
	v_mov_b32_e32 v201, 0
	v_mov_b32_e32 v202, 0
	v_mov_b32_e32 v203, 0
	v_mov_b32_e32 v204, 0
	v_mov_b32_e32 v205, 0
	v_mov_b32_e32 v206, 0
	v_mov_b32_e32 v207, 0
	v_mov_b32_e32 v208, 0
	v_mov_b32_e32 v209, 0
	v_mov_b32_e32 v210, 0
	v_mov_b32_e32 v211, 0
	s_mov_b32 s93, 0xff800000
	s_mov_b32 s94, 0xff800000
	s_cmp_lt_u32 s35, 0x1000
	s_cbranch_scc0 .Lstg_b_pro
	s_barrier

; #define SBAR() __builtin_amdgcn_sched_barrier(0)
; template <int N> DI void wait_lgkm() { asm volatile("s_waitcnt lgkmcnt(%0)" :: "i"(N) : "memory"); }
; template <int DQK, int MODE>
; DI void attn_body(const AttnArgs& a, char* lds) {
;     ...
;     auto qkt = [&](f32x16& p0, f32x16& p1, const int kofs) {
;         p0 = f32x16{}; p1 = f32x16{};
;         int kc[NB];
; #pragma unroll
;         for (int i = 0; i < NB; ++i) kc[i] = kb[i] + kofs;
;         bf16x8 fk[2][2]; bf16x8 fq[2];
;         auto rd = [&](auto ic) { constexpr int d0 = decltype(ic)::value; constexpr int sl = d0 & 1;
;             dsr128<(d0 / NB) * (NB * 32)>(fk[sl][0], kc[d0 % NB]); dsr128<(d0 / NB) * (NB * 32) + 32 * KROWB>(fk[sl][1], kc[d0 % NB]);
;             if constexpr (MODE == 2 && d0 >= NQR) dsr128<(d0 - NQR) * 1024>(fq[sl], qra); };
;         rd(std::integral_constant<int, 0>{});
;         cfor<0, ND0>([&](auto ic) { constexpr int d0 = decltype(ic)::value; constexpr int sl = d0 & 1;
;             if constexpr (d0 + 1 < ND0) { rd(std::integral_constant<int, d0 + 1>{}); wait_lgkm<(MODE == 2 && d0 + 1 >= NQR) ? 3 : 2>(); }
;             else wait_lgkm<0>();
;             SBAR();
;             bf16x8 qf; if constexpr (MODE == 2 && d0 >= NQR) qf = fq[sl]; else qf = qr[d0 < NQR ? d0 : 0];
;             p0 = __builtin_amdgcn_mfma_f32_32x32x16_bf16(fk[sl][0], qf, p0, 0, 0, 0);
;             p1 = __builtin_amdgcn_mfma_f32_32x32x16_bf16(fk[sl][1], qf, p1, 0, 0, 0); });
;     };
;     ...
;         } else {
;             float pmax = p0[0];
; #pragma unroll
;             for (int r = 1; r < 16; ++r) pmax = fmaxf(pmax, p0[r]);
; #pragma unroll
;             for (int r = 0; r < 16; ++r) pmax = fmaxf(pmax, p1[r]);
;             { auto rr = __builtin_amdgcn_permlane32_swap(__float_as_uint(pmax), __float_as_uint(pmax), false, false);
;               pmax = fmaxf(__uint_as_float(rr[0]), __uint_as_float(rr[1])); }
;             if (__builtin_expect(__all((pmax - m_reg) * C <= THR_L2), 1)) { mn = m_reg; alpha = 1.f; }
;             else { mn = fmaxf(m_reg, pmax); alpha = __builtin_amdgcn_exp2f((m_reg - mn) * C); m_reg = mn; }
;             const float mnC = -mn * C;
; #pragma unroll
;             for (int r = 0; r < 16; ++r) { p0[r] = fmaf(p0[r], C, mnC); p1[r] = fmaf(p1[r], C, mnC); }
; #pragma unroll
;             for (int r = 0; r < 16; ++r) p0[r] = __builtin_amdgcn_exp2f(p0[r]);
.LBB0_811:
	v_add_u32_e32 v74, s49, v145
	ds_read_b128 v[66:69], v74 offset:0
	ds_read_b128 v[70:73], v74 offset:0x2000
	v_add_u32_e32 v75, s49, v146
	ds_read_b128 v[158:161], v75 offset:0
	ds_read_b128 v[162:165], v75 offset:0x2000
	s_waitcnt lgkmcnt(2)
	v_add_u32_e32 v157, s49, v147
	v_add_u32_e32 v174, s49, v148
	v_add_u32_e32 v175, s49, v150
	v_add_u32_e32 v176, s49, v151
	v_add_u32_e32 v177, s49, v152
	v_add_u32_e32 v178, s49, v153
	v_mfma_f32_32x32x16_bf16 v[82:97], v[66:69], v[98:101], v[196:211]
	ds_read_b128 v[166:169], v157 offset:0
	ds_read_b128 v[170:173], v157 offset:0x2000
	s_waitcnt lgkmcnt(2)
	v_mfma_f32_32x32x16_bf16 v[66:81], v[70:73], v[98:101], v[196:211]
	v_mfma_f32_32x32x16_bf16 v[82:97], v[158:161], v[102:105], v[82:97]
	ds_read_b128 v[158:161], v174 offset:0
	v_mfma_f32_32x32x16_bf16 v[66:81], v[162:165], v[102:105], v[66:81]
	ds_read_b128 v[162:165], v174 offset:0x2000
	s_waitcnt lgkmcnt(2)
	v_mfma_f32_32x32x16_bf16 v[82:97], v[166:169], v[106:109], v[82:97]
	ds_read_b128 v[166:169], v175 offset:0
	v_mfma_f32_32x32x16_bf16 v[66:81], v[170:173], v[106:109], v[66:81]
	ds_read_b128 v[170:173], v175 offset:0x2000
	s_waitcnt lgkmcnt(2)
	v_mfma_f32_32x32x16_bf16 v[82:97], v[158:161], v[110:113], v[82:97]
	ds_read_b128 v[158:161], v176 offset:0
	v_mfma_f32_32x32x16_bf16 v[66:81], v[162:165], v[110:113], v[66:81]
	ds_read_b128 v[162:165], v176 offset:0x2000
	s_waitcnt lgkmcnt(2)
	v_mfma_f32_32x32x16_bf16 v[82:97], v[166:169], v[114:117], v[82:97]
	ds_read_b128 v[166:169], v177 offset:0
	v_mfma_f32_32x32x16_bf16 v[66:81], v[170:173], v[114:117], v[66:81]
	ds_read_b128 v[170:173], v177 offset:0x2000
	s_waitcnt lgkmcnt(2)
	v_mfma_f32_32x32x16_bf16 v[82:97], v[158:161], v[118:121], v[82:97]
	ds_read_b128 v[158:161], v178 offset:0
	v_mfma_f32_32x32x16_bf16 v[66:81], v[162:165], v[118:121], v[66:81]
	ds_read_b128 v[162:165], v178 offset:0x2000
	s_waitcnt lgkmcnt(2)
	v_mfma_f32_32x32x16_bf16 v[82:97], v[166:169], v[122:125], v[82:97]
	s_waitcnt lgkmcnt(0)
	v_mfma_f32_32x32x16_bf16 v[66:81], v[170:173], v[122:125], v[66:81]
	v_mfma_f32_32x32x16_bf16 v[82:97], v[158:161], v[126:129], v[82:97]
	v_mfma_f32_32x32x16_bf16 v[66:81], v[162:165], v[126:129], v[66:81]
	s_nop 9
	v_max_f32_e32 v158, v82, v83
	v_max3_f32 v158, v158, v84, v85
	v_max3_f32 v158, v158, v86, v87
	v_max3_f32 v158, v158, v88, v89
	v_max3_f32 v158, v158, v90, v91
	v_max3_f32 v158, v158, v92, v93
	v_max3_f32 v158, v158, v94, v95
	v_max3_f32 v158, v158, v96, v97
	v_max3_f32 v158, v158, v66, v67
	v_max3_f32 v158, v158, v68, v69
	v_max3_f32 v158, v158, v70, v71
	v_max3_f32 v158, v158, v72, v73
	v_max3_f32 v158, v158, v74, v75
	v_max3_f32 v158, v158, v76, v77
	v_max3_f32 v158, v158, v78, v79
	v_max3_f32 v158, v158, v80, v81
	v_mov_b32_e32 v159, v158
	s_nop 1
	v_permlane32_swap_b32_e32 v158, v159
	v_max_f32_e32 v158, v158, v159
	v_cmp_ge_f32_e32 vcc, s94, v158
	s_mov_b32 s32, 0
	s_cmp_eq_u64 vcc, exec
	s_cbranch_scc1 .Lfold_b_fast
	v_max_f32_e32 v159, s93, v158
	s_mov_b32 s93, 0
	s_mov_b32 s94, 0x4138aa3b
	v_sub_f32_e32 v82, v82, v159
	v_sub_f32_e32 v83, v83, v159
	v_sub_f32_e32 v84, v84, v159
	v_sub_f32_e32 v85, v85, v159
	v_sub_f32_e32 v86, v86, v159
	v_sub_f32_e32 v87, v87, v159
	v_sub_f32_e32 v88, v88, v159
	v_sub_f32_e32 v89, v89, v159
	v_sub_f32_e32 v90, v90, v159
	v_sub_f32_e32 v91, v91, v159
	v_sub_f32_e32 v92, v92, v159
	v_sub_f32_e32 v93, v93, v159
	v_sub_f32_e32 v94, v94, v159
	v_sub_f32_e32 v95, v95, v159
	v_sub_f32_e32 v96, v96, v159
	v_sub_f32_e32 v97, v97, v159
	v_sub_f32_e32 v66, v66, v159
	v_sub_f32_e32 v67, v67, v159
	v_sub_f32_e32 v68, v68, v159
	v_sub_f32_e32 v69, v69, v159
	v_sub_f32_e32 v70, v70, v159
	v_sub_f32_e32 v71, v71, v159
	v_sub_f32_e32 v72, v72, v159
	v_sub_f32_e32 v73, v73, v159
	v_sub_f32_e32 v74, v74, v159
	v_sub_f32_e32 v75, v75, v159
	v_sub_f32_e32 v76, v76, v159
	v_sub_f32_e32 v77, v77, v159
	v_sub_f32_e32 v78, v78, v159
	v_sub_f32_e32 v79, v79, v159
	v_sub_f32_e32 v80, v80, v159
	v_sub_f32_e32 v81, v81, v159
	v_sub_f32_e32 v196, v196, v159
	v_sub_f32_e32 v197, v197, v159
	v_sub_f32_e32 v198, v198, v159
	v_sub_f32_e32 v199, v199, v159
	v_sub_f32_e32 v200, v200, v159
	v_sub_f32_e32 v201, v201, v159
	v_sub_f32_e32 v202, v202, v159
	v_sub_f32_e32 v203, v203, v159
	v_sub_f32_e32 v204, v204, v159
	v_sub_f32_e32 v205, v205, v159
	v_sub_f32_e32 v206, v206, v159
	v_sub_f32_e32 v207, v207, v159
	v_sub_f32_e32 v208, v208, v159
	v_sub_f32_e32 v209, v209, v159
	v_sub_f32_e32 v210, v210, v159
	v_sub_f32_e32 v211, v211, v159
	v_exp_f32_e64 v157, -v159 clamp
	s_mov_b32 s32, 1
.Lfold_b_fast:
	v_mov_b32_e32 v158, v81
	s_waitcnt vmcnt(0)
	s_barrier
	s_cmp_lt_u32 s36, s47
	s_cbranch_scc0 .Lstg_b_nov
	s_xor_b32 s46, s49, 0x4000
	s_add_i32 s46, s35, s46
	s_mov_b32 s52, s89
	s_mov_b32 s53, s90
	s_mov_b32 m0, s46
	s_nop 0
	global_load_lds_dwordx4 v216, s[52:53]
	s_add_i32 m0, s46, 0x2000
	s_nop 0
	global_load_lds_dwordx4 v217, s[52:53]
